# v21 plus wave-wide xor-butterfly sums via v_permlane32/16_swap and DPP adds instead of six ds_bpermute round trips (fix_l3, norm_rows, final_norm), bit-identical pairing
# speedup vs baseline: 1.0059x; 1.0058x over previous
.LBB0_108:
	global_load_dwordx4 v[6:9], v[16:17], off offset:-4096
	global_load_dwordx4 v[2:5], v[16:17], off offset:-4080
	global_load_dwordx4 v[26:29], v[16:17], off offset:-2048
	global_load_dwordx4 v[10:13], v[16:17], off offset:-2032
	global_load_dwordx4 v[30:33], v[16:17], off
	global_load_dwordx4 v[34:37], v[16:17], off offset:16
	global_load_dwordx4 v[38:41], v[16:17], off offset:2048
	global_load_dwordx4 v[42:45], v[16:17], off offset:2064
	v_add_u32_e32 v14, s88, v14
	v_cmp_lt_i32_e32 vcc, s10, v14
	s_or_b64 s[4:5], vcc, s[4:5]
	v_lshl_add_u64 v[16:17], v[16:17], 0, s[6:7]
	s_waitcnt vmcnt(7)
	v_mul_f32_e32 v15, v7, v7
	s_waitcnt vmcnt(6)
	v_mul_f32_e32 v25, v3, v3
	s_waitcnt vmcnt(5)
	v_mul_f32_e32 v64, v27, v27
	v_fmac_f32_e32 v15, v6, v6
	v_fmac_f32_e32 v25, v2, v2
	s_waitcnt vmcnt(4)
	v_mul_f32_e32 v65, v11, v11
	s_waitcnt vmcnt(3)
	v_pk_mul_f32 v[50:51], v[30:31], v[30:31]
	s_waitcnt vmcnt(2)
	v_pk_mul_f32 v[52:53], v[34:35], v[34:35]
	v_fmac_f32_e32 v64, v26, v26
	v_fmac_f32_e32 v15, v8, v8
	v_fmac_f32_e32 v25, v4, v4
	v_pk_mul_f32 v[46:47], v[32:33], v[32:33]
	v_pk_mul_f32 v[48:49], v[36:37], v[36:37]
	v_fmac_f32_e32 v65, v10, v10
	v_mov_b32_e32 v62, v50
	v_mov_b32_e32 v63, v52
	v_mov_b32_e32 v52, v51
	v_fmac_f32_e32 v64, v28, v28
	v_fmac_f32_e32 v15, v9, v9
	v_fmac_f32_e32 v25, v5, v5
	s_waitcnt vmcnt(1)
	v_pk_mul_f32 v[58:59], v[38:39], v[38:39]
	s_waitcnt vmcnt(0)
	v_pk_mul_f32 v[60:61], v[42:43], v[42:43]
	v_mov_b32_e32 v50, v46
	v_mov_b32_e32 v51, v48
	v_fmac_f32_e32 v65, v12, v12
	v_pk_add_f32 v[52:53], v[62:63], v[52:53]
	v_fmac_f32_e32 v64, v29, v29
	v_add_f32_e32 v15, v15, v25
	v_pk_mul_f32 v[54:55], v[40:41], v[40:41]
	v_pk_mul_f32 v[56:57], v[44:45], v[44:45]
	v_mov_b32_e32 v48, v47
	v_mov_b32_e32 v46, v58
	v_mov_b32_e32 v47, v60
	v_mov_b32_e32 v60, v59
	v_fmac_f32_e32 v65, v13, v13
	v_pk_add_f32 v[50:51], v[52:53], v[50:51]
	v_add_f32_e32 v15, v15, v64
	v_mov_b32_e32 v58, v54
	v_mov_b32_e32 v59, v56
	v_pk_add_f32 v[46:47], v[46:47], v[60:61]
	v_pk_add_f32 v[48:49], v[50:51], v[48:49]
	v_add_f32_e32 v15, v15, v65
	v_mov_b32_e32 v56, v55
	v_pk_add_f32 v[46:47], v[46:47], v[58:59]
	v_add_f32_e32 v15, v15, v48
	v_pk_add_f32 v[46:47], v[46:47], v[56:57]
	v_add_f32_e32 v15, v15, v49
	v_add_f32_e32 v15, v15, v46
	v_add_f32_e32 v15, v15, v47
	v_mov_b32_e32 v25, v15
	s_nop 1
	v_permlane32_swap_b32_e32 v25, v15
	v_add_f32_e32 v15, v15, v25
	v_mov_b32_e32 v25, v15
	s_nop 1
	v_permlane16_swap_b32_e32 v25, v15
	v_add_f32_e32 v15, v15, v25
	s_nop 1
	v_add_f32_dpp v15, v15, v15 row_ror:8 row_mask:0xf bank_mask:0xf
	s_nop 1
	v_add_f32_dpp v15, v15, v15 row_ror:4 row_mask:0xf bank_mask:0xf
	s_nop 1
	v_add_f32_dpp v15, v15, v15 quad_perm:[2,3,0,1] row_mask:0xf bank_mask:0xf
	s_nop 1
	v_add_f32_dpp v15, v15, v15 quad_perm:[1,0,3,2] row_mask:0xf bank_mask:0xf
	s_nop 1
	v_fmamk_f32 v15, v15, 0x3a000000, v203
	v_mul_f32_e32 v25, 0x4b800000, v15
	v_cmp_gt_f32_e32 vcc, s2, v15
	s_nop 1
	v_cndmask_b32_e32 v15, v15, v25, vcc
	v_rsq_f32_e32 v15, v15
	s_nop 0
	v_mul_f32_e32 v25, 0x45800000, v15
	v_cndmask_b32_e32 v15, v15, v25, vcc
	v_mul_f32_e32 v5, v5, v15
	v_mul_f32_e32 v6, v6, v15
	v_mul_f32_e32 v7, v7, v15
	v_mul_f32_e32 v8, v8, v15
	v_mul_f32_e32 v9, v9, v15
	v_mul_f32_e32 v25, v2, v15
	v_mul_f32_e32 v46, v3, v15
	v_mul_f32_e32 v47, v4, v15
	v_cvt_pk_bf16_f32 v2, v6, v7
	v_cvt_pk_bf16_f32 v3, v8, v9
	v_cvt_pk_bf16_f32 v4, v25, v46
	v_cvt_pk_bf16_f32 v5, v47, v5
	v_mul_f32_e32 v26, v26, v15
	v_mul_f32_e32 v27, v27, v15
	v_mul_f32_e32 v28, v28, v15
	v_mul_f32_e32 v29, v29, v15
	v_mul_f32_e32 v10, v10, v15
	v_mul_f32_e32 v11, v11, v15
	v_mul_f32_e32 v12, v12, v15
	v_mul_f32_e32 v13, v13, v15
	global_store_dwordx4 v[18:19], v[2:5], off
	v_mul_f32_e32 v30, v30, v15
	v_mul_f32_e32 v31, v31, v15
	v_cvt_pk_bf16_f32 v2, v26, v27
	v_cvt_pk_bf16_f32 v3, v28, v29
	v_cvt_pk_bf16_f32 v4, v10, v11
	v_cvt_pk_bf16_f32 v5, v12, v13
	v_mul_f32_e32 v32, v32, v15
	v_mul_f32_e32 v33, v33, v15
	v_mul_f32_e32 v34, v34, v15
	v_mul_f32_e32 v35, v35, v15
	v_mul_f32_e32 v36, v36, v15
	v_mul_f32_e32 v37, v37, v15
	global_store_dwordx4 v[18:19], v[2:5], off offset:1024
	v_mul_f32_e32 v38, v38, v15
	v_mul_f32_e32 v39, v39, v15
	v_cvt_pk_bf16_f32 v2, v30, v31
	v_cvt_pk_bf16_f32 v3, v32, v33
	v_cvt_pk_bf16_f32 v4, v34, v35
	v_cvt_pk_bf16_f32 v5, v36, v37
	v_mul_f32_e32 v40, v40, v15
	v_mul_f32_e32 v41, v41, v15
	v_mul_f32_e32 v42, v42, v15
	v_mul_f32_e32 v43, v43, v15
	v_mul_f32_e32 v44, v44, v15
	v_mul_f32_e32 v15, v45, v15
	global_store_dwordx4 v[18:19], v[2:5], off offset:2048
	s_nop 1
	v_cvt_pk_bf16_f32 v2, v38, v39
	v_cvt_pk_bf16_f32 v3, v40, v41
	v_cvt_pk_bf16_f32 v4, v42, v43
	v_cvt_pk_bf16_f32 v5, v44, v15
	global_store_dwordx4 v[18:19], v[2:5], off offset:3072
	v_lshl_add_u64 v[18:19], v[18:19], 0, s[8:9]
	s_andn2_b64 exec, exec, s[4:5]
	s_cbranch_execnz .LBB0_108

.LBB0_780:
	s_or_b64 exec, exec, s[10:11]
	v_lshlrev_b64 v[38:39], 10, v[34:35]
	s_waitcnt vmcnt(1)
	v_and_b32_e32 v35, 0xffff0000, v14
	v_lshlrev_b32_e32 v0, 16, v14
	v_mul_f32_e32 v48, v35, v35
	v_fmac_f32_e32 v48, v0, v0
	v_lshlrev_b32_e32 v49, 16, v15
	v_fmac_f32_e32 v48, v49, v49
	v_and_b32_e32 v50, 0xffff0000, v15
	v_and_b32_e32 v15, 0xffff0000, v16
	v_lshlrev_b32_e32 v14, 16, v16
	v_fmac_f32_e32 v48, v50, v50
	v_pk_mul_f32 v[46:47], v[14:15], v[14:15]
	s_mov_b32 s2, 0x800000
	v_add_f32_e32 v16, v46, v48
	v_add_f32_e32 v48, v47, v16
	v_and_b32_e32 v47, 0xffff0000, v17
	v_lshlrev_b32_e32 v46, 16, v17
	v_pk_mul_f32 v[16:17], v[46:47], v[46:47]
	s_nop 0
	v_add_f32_e32 v16, v16, v48
	v_add_f32_e32 v16, v17, v16
	v_mov_b32_e32 v17, v16
	s_nop 1
	v_permlane32_swap_b32_e32 v17, v16
	v_add_f32_e32 v16, v16, v17
	v_mov_b32_e32 v17, v16
	s_nop 1
	v_permlane16_swap_b32_e32 v17, v16
	v_add_f32_e32 v16, v16, v17
	s_nop 1
	v_add_f32_dpp v16, v16, v16 row_ror:8 row_mask:0xf bank_mask:0xf
	s_nop 1
	v_add_f32_dpp v16, v16, v16 row_ror:4 row_mask:0xf bank_mask:0xf
	s_nop 1
	v_add_f32_dpp v16, v16, v16 quad_perm:[2,3,0,1] row_mask:0xf bank_mask:0xf
	s_nop 1
	v_add_f32_dpp v16, v16, v16 quad_perm:[1,0,3,2] row_mask:0xf bank_mask:0xf
	s_nop 1
	v_fmamk_f32 v16, v16, 0x3b000000, v203
	v_cmp_gt_f32_e32 vcc, s2, v16
	v_mul_f32_e32 v17, 0x4b800000, v16
	s_nop 0
	v_cndmask_b32_e32 v16, v16, v17, vcc
	v_rsq_f32_e32 v16, v16
	s_nop 0
	v_mul_f32_e32 v17, 0x45800000, v16
	v_cndmask_b32_e32 v16, v16, v17, vcc
	v_mul_f32_e32 v17, v16, v35
	v_mul_f32_e32 v46, v16, v46
	v_mul_f32_e32 v47, v16, v47
	v_mul_f32_e32 v0, v16, v0
	v_mul_f32_e32 v35, v16, v49
	v_mul_f32_e32 v48, v16, v50
	v_mul_f32_e32 v49, v16, v14
	v_mul_f32_e32 v50, v16, v15
	v_cvt_pk_bf16_f32 v14, v0, v17
	v_cvt_pk_bf16_f32 v15, v35, v48
	v_cvt_pk_bf16_f32 v16, v49, v50
	v_cvt_pk_bf16_f32 v17, v46, v47
	v_lshl_add_u64 v[46:47], v[26:27], 0, v[38:39]
	global_store_dwordx4 v[46:47], v[14:17], off
	s_waitcnt vmcnt(1)
	v_lshlrev_b32_e32 v0, 16, v10
	v_lshlrev_b32_e32 v35, 16, v11
	v_and_b32_e32 v16, 0xffff0000, v10
	v_mul_f32_e32 v17, v16, v16
	v_fmac_f32_e32 v17, v0, v0
	v_fmac_f32_e32 v17, v35, v35
	v_and_b32_e32 v46, 0xffff0000, v11
	v_and_b32_e32 v11, 0xffff0000, v12
	v_lshlrev_b32_e32 v10, 16, v12
	v_fmac_f32_e32 v17, v46, v46
	v_pk_mul_f32 v[14:15], v[10:11], v[10:11]
	s_nop 0
	v_add_f32_e32 v12, v14, v17
	v_add_f32_e32 v17, v15, v12
	v_and_b32_e32 v15, 0xffff0000, v13
	v_lshlrev_b32_e32 v14, 16, v13
	v_pk_mul_f32 v[12:13], v[14:15], v[14:15]
	s_nop 0
	v_add_f32_e32 v12, v12, v17
	v_add_f32_e32 v12, v13, v12
	v_mov_b32_e32 v13, v12
	s_nop 1
	v_permlane32_swap_b32_e32 v13, v12
	v_add_f32_e32 v12, v12, v13
	v_mov_b32_e32 v13, v12
	s_nop 1
	v_permlane16_swap_b32_e32 v13, v12
	v_add_f32_e32 v12, v12, v13
	s_nop 1
	v_add_f32_dpp v12, v12, v12 row_ror:8 row_mask:0xf bank_mask:0xf
	s_nop 1
	v_add_f32_dpp v12, v12, v12 row_ror:4 row_mask:0xf bank_mask:0xf
	s_nop 1
	v_add_f32_dpp v12, v12, v12 quad_perm:[2,3,0,1] row_mask:0xf bank_mask:0xf
	s_nop 1
	v_add_f32_dpp v12, v12, v12 quad_perm:[1,0,3,2] row_mask:0xf bank_mask:0xf
	s_nop 1
	v_fmamk_f32 v12, v12, 0x3b000000, v203
	v_cmp_gt_f32_e32 vcc, s2, v12
	v_mul_f32_e32 v13, 0x4b800000, v12
	s_nop 0
	v_cndmask_b32_e32 v12, v12, v13, vcc
	v_rsq_f32_e32 v12, v12
	s_nop 0
	v_mul_f32_e32 v13, 0x45800000, v12
	v_cndmask_b32_e32 v12, v12, v13, vcc
	v_mul_f32_e32 v13, v12, v16
	v_mul_f32_e32 v14, v12, v14
	v_mul_f32_e32 v15, v12, v15
	v_mul_f32_e32 v0, v12, v0
	v_mul_f32_e32 v16, v12, v35
	v_mul_f32_e32 v17, v12, v46
	v_mul_f32_e32 v35, v12, v10
	v_mul_f32_e32 v46, v12, v11
	v_cvt_pk_bf16_f32 v10, v0, v13
	v_cvt_pk_bf16_f32 v11, v16, v17
	v_cvt_pk_bf16_f32 v12, v35, v46
	v_cvt_pk_bf16_f32 v13, v14, v15
	v_lshl_add_u64 v[14:15], v[28:29], 0, v[38:39]
	global_store_dwordx4 v[14:15], v[10:13], off
	s_and_saveexec_b64 s[10:11], s[0:1]
	s_cbranch_execz .LBB0_782
	s_movk_i32 s2, 0x2200
	v_mad_i64_i32 v[10:11], s[14:15], v34, s2, 0
	v_lshlrev_b32_e32 v12, 16, v44
	v_lshlrev_b32_e32 v0, 16, v45
	v_mul_f32_e32 v13, v37, v12
	v_lshl_add_u64 v[10:11], v[24:25], 0, v[10:11]
	v_fma_f32 v13, v36, v0, -v13
	v_add_co_u32_e32 v10, vcc, 0x2000, v10
	v_mul_f32_e32 v0, v37, v0
	s_nop 0
	v_addc_co_u32_e32 v11, vcc, 0, v11, vcc
	v_fmac_f32_e32 v0, v36, v12
	v_cvt_pk_bf16_f32 v13, v13, v13
	global_store_short v[10:11], v13, off
	v_cvt_pk_bf16_f32 v0, v0, v0
	global_store_short v[10:11], v0, off offset:64
.LBB0_782:
	s_or_b64 exec, exec, s[10:11]
	s_and_saveexec_b64 s[10:11], s[4:5]
	s_cbranch_execz .LBB0_773
	v_lshlrev_b64 v[10:11], 10, v[30:31]
	v_and_b32_e32 v31, 0xffff0000, v6
	v_lshlrev_b32_e32 v0, 16, v6
	v_mul_f32_e32 v16, v31, v31
	v_fmac_f32_e32 v16, v0, v0
	v_lshlrev_b32_e32 v34, 16, v7
	v_fmac_f32_e32 v16, v34, v34
	v_and_b32_e32 v35, 0xffff0000, v7
	v_and_b32_e32 v13, 0xffff0000, v8
	v_lshlrev_b32_e32 v12, 16, v8
	v_fmac_f32_e32 v16, v35, v35
	v_pk_mul_f32 v[14:15], v[12:13], v[12:13]
	s_mov_b32 s2, 0x800000
	v_add_f32_e32 v14, v14, v16
	v_add_f32_e32 v36, v15, v14
	v_and_b32_e32 v15, 0xffff0000, v9
	v_lshlrev_b32_e32 v14, 16, v9
	v_pk_mul_f32 v[16:17], v[14:15], v[14:15]
	s_nop 0
	v_add_f32_e32 v16, v16, v36
	v_add_f32_e32 v16, v17, v16
	v_mov_b32_e32 v17, v16
	s_nop 1
	v_permlane32_swap_b32_e32 v17, v16
	v_add_f32_e32 v16, v16, v17
	v_mov_b32_e32 v17, v16
	s_nop 1
	v_permlane16_swap_b32_e32 v17, v16
	v_add_f32_e32 v16, v16, v17
	s_nop 1
	v_add_f32_dpp v16, v16, v16 row_ror:8 row_mask:0xf bank_mask:0xf
	s_nop 1
	v_add_f32_dpp v16, v16, v16 row_ror:4 row_mask:0xf bank_mask:0xf
	s_nop 1
	v_add_f32_dpp v16, v16, v16 quad_perm:[2,3,0,1] row_mask:0xf bank_mask:0xf
	s_nop 1
	v_add_f32_dpp v16, v16, v16 quad_perm:[1,0,3,2] row_mask:0xf bank_mask:0xf
	s_nop 1
	v_fmamk_f32 v16, v16, 0x3b000000, v203
	v_cmp_gt_f32_e32 vcc, s2, v16
	v_mul_f32_e32 v17, 0x4b800000, v16
	s_nop 0
	v_cndmask_b32_e32 v16, v16, v17, vcc
	v_rsq_f32_e32 v16, v16
	s_nop 0
	v_mul_f32_e32 v17, 0x45800000, v16
	v_cndmask_b32_e32 v16, v16, v17, vcc
	v_mul_f32_e32 v17, v16, v31
	v_mul_f32_e32 v31, v16, v34
	v_mul_f32_e32 v0, v16, v0
	v_mul_f32_e32 v34, v16, v35
	v_mul_f32_e32 v35, v16, v12
	v_mul_f32_e32 v36, v16, v13
	v_mul_f32_e32 v37, v16, v14
	v_mul_f32_e32 v15, v16, v15
	v_cvt_pk_bf16_f32 v12, v0, v17
	v_cvt_pk_bf16_f32 v13, v31, v34
	v_lshl_add_u64 v[16:17], v[26:27], 0, v[10:11]
	v_and_b32_e32 v31, 0xffff0000, v2
	v_cvt_pk_bf16_f32 v14, v35, v36
	v_cvt_pk_bf16_f32 v15, v37, v15
	global_store_dwordx4 v[16:17], v[12:15], off
	v_lshlrev_b32_e32 v0, 16, v2
	v_mul_f32_e32 v16, v31, v31
	v_fmac_f32_e32 v16, v0, v0
	v_lshlrev_b32_e32 v34, 16, v3
	v_fmac_f32_e32 v16, v34, v34
	v_and_b32_e32 v35, 0xffff0000, v3
	v_and_b32_e32 v13, 0xffff0000, v4
	v_lshlrev_b32_e32 v12, 16, v4
	v_fmac_f32_e32 v16, v35, v35
	v_pk_mul_f32 v[14:15], v[12:13], v[12:13]
	v_lshl_add_u64 v[10:11], v[28:29], 0, v[10:11]
	v_add_f32_e32 v14, v14, v16
	v_add_f32_e32 v36, v15, v14
	v_and_b32_e32 v15, 0xffff0000, v5
	v_lshlrev_b32_e32 v14, 16, v5
	v_pk_mul_f32 v[16:17], v[14:15], v[14:15]
	s_nop 0
	v_add_f32_e32 v16, v16, v36
	v_add_f32_e32 v16, v17, v16
	v_mov_b32_e32 v17, v16
	s_nop 1
	v_permlane32_swap_b32_e32 v17, v16
	v_add_f32_e32 v16, v16, v17
	v_mov_b32_e32 v17, v16
	s_nop 1
	v_permlane16_swap_b32_e32 v17, v16
	v_add_f32_e32 v16, v16, v17
	s_nop 1
	v_add_f32_dpp v16, v16, v16 row_ror:8 row_mask:0xf bank_mask:0xf
	s_nop 1
	v_add_f32_dpp v16, v16, v16 row_ror:4 row_mask:0xf bank_mask:0xf
	s_nop 1
	v_add_f32_dpp v16, v16, v16 quad_perm:[2,3,0,1] row_mask:0xf bank_mask:0xf
	s_nop 1
	v_add_f32_dpp v16, v16, v16 quad_perm:[1,0,3,2] row_mask:0xf bank_mask:0xf
	s_nop 1
	v_fmamk_f32 v16, v16, 0x3b000000, v203
	v_cmp_gt_f32_e32 vcc, s2, v16
	v_mul_f32_e32 v17, 0x4b800000, v16
	s_nop 0
	v_cndmask_b32_e32 v16, v16, v17, vcc
	v_rsq_f32_e32 v16, v16
	s_nop 0
	v_mul_f32_e32 v17, 0x45800000, v16
	v_cndmask_b32_e32 v16, v16, v17, vcc
	v_mul_f32_e32 v15, v16, v15
	v_mul_f32_e32 v0, v16, v0
	v_mul_f32_e32 v17, v16, v31
	v_mul_f32_e32 v31, v16, v34
	v_mul_f32_e32 v34, v16, v35
	v_mul_f32_e32 v35, v16, v12
	v_mul_f32_e32 v36, v16, v13
	v_mul_f32_e32 v37, v16, v14
	v_cvt_pk_bf16_f32 v12, v0, v17
	v_cvt_pk_bf16_f32 v13, v31, v34
	v_cvt_pk_bf16_f32 v14, v35, v36
	v_cvt_pk_bf16_f32 v15, v37, v15
	global_store_dwordx4 v[10:11], v[12:15], off
	s_and_b64 exec, exec, s[0:1]
	s_cbranch_execz .LBB0_773
	v_and_b32_e32 v12, 0xffff0000, v44
	v_and_b32_e32 v0, 0xffff0000, v45
	v_mul_f32_e32 v10, v33, v12
	v_fma_f32 v10, v32, v0, -v10
	s_movk_i32 s2, 0x2200
	v_cvt_pk_bf16_f32 v13, v10, v10
	v_mad_i64_i32 v[10:11], s[4:5], v30, s2, v[24:25]
	v_add_co_u32_e32 v10, vcc, 0x2000, v10
	v_mul_f32_e32 v0, v33, v0
	s_nop 0
	v_addc_co_u32_e32 v11, vcc, 0, v11, vcc
	v_fmac_f32_e32 v0, v32, v12
	global_store_short v[10:11], v13, off
	v_cvt_pk_bf16_f32 v0, v0, v0
	global_store_short v[10:11], v0, off offset:64
	s_branch .LBB0_773

.LBB0_1421:
	global_load_dwordx4 v[32:35], v[42:43], off
	global_load_dwordx4 v[36:39], v[42:43], off offset:1024
	global_load_dwordx4 v[50:53], v[42:43], off offset:2048
	global_load_dwordx4 v[54:57], v[42:43], off offset:3072
	global_load_dwordx4 v[58:61], v[42:43], off offset:-3072
	global_load_dwordx4 v[62:65], v[42:43], off offset:-4096
	global_load_dwordx4 v[66:69], v[42:43], off offset:-2048
	global_load_dwordx4 v[70:73], v[42:43], off offset:-1024
	v_add_u32_e32 v40, s88, v40
	v_cmp_lt_i32_e64 s[0:1], s5, v40
	s_or_b64 s[2:3], s[0:1], s[2:3]
	s_waitcnt vmcnt(7)
	v_mov_b32_e32 v76, v33
	s_waitcnt vmcnt(6)
	v_mov_b32_e32 v77, v37
	s_waitcnt vmcnt(5)
	v_mov_b32_e32 v82, v51
	s_waitcnt vmcnt(4)
	v_mov_b32_e32 v83, v55
	s_waitcnt vmcnt(3)
	v_pk_mul_f32 v[86:87], v[58:59], v[58:59]
	s_waitcnt vmcnt(2)
	v_pk_mul_f32 v[90:91], v[62:63], v[62:63]
	v_mov_b32_e32 v74, v32
	v_mov_b32_e32 v75, v36
	v_mov_b32_e32 v80, v50
	v_mov_b32_e32 v81, v54
	v_pk_mul_f32 v[88:89], v[60:61], v[60:61]
	v_pk_mul_f32 v[92:93], v[64:65], v[64:65]
	s_waitcnt vmcnt(1)
	v_pk_mul_f32 v[94:95], v[66:67], v[66:67]
	v_pk_mul_f32 v[76:77], v[76:77], v[76:77]
	v_pk_mul_f32 v[82:83], v[82:83], v[82:83]
	v_add_f32_e32 v86, v86, v87
	v_add_f32_e32 v87, v90, v91
	v_mov_b32_e32 v78, v34
	v_mov_b32_e32 v79, v38
	v_pk_mul_f32 v[96:97], v[68:69], v[68:69]
	s_waitcnt vmcnt(0)
	v_pk_mul_f32 v[98:99], v[70:71], v[70:71]
	v_add_f32_e32 v90, v94, v95
	v_pk_fma_f32 v[74:75], v[74:75], v[74:75], v[76:77]
	v_pk_fma_f32 v[76:77], v[80:81], v[80:81], v[82:83]
	v_add_f32_e32 v80, v86, v88
	v_add_f32_e32 v81, v87, v92
	v_pk_mul_f32 v[100:101], v[72:73], v[72:73]
	v_add_f32_e32 v91, v98, v99
	v_add_f32_e32 v82, v90, v96
	v_pk_fma_f32 v[74:75], v[78:79], v[78:79], v[74:75]
	v_add_f32_e32 v78, v80, v89
	v_add_f32_e32 v79, v81, v93
	v_add_f32_e32 v83, v91, v100
	v_add_f32_e32 v80, v82, v97
	v_add_f32_e32 v78, v79, v78
	v_mov_b32_e32 v102, v35
	v_mov_b32_e32 v103, v39
	v_add_f32_e32 v81, v83, v101
	v_add_f32_e32 v78, v78, v80
	v_mov_b32_e32 v84, v52
	v_mov_b32_e32 v85, v56
	v_pk_fma_f32 v[74:75], v[102:103], v[102:103], v[74:75]
	v_add_f32_e32 v78, v78, v81
	v_mov_b32_e32 v104, v53
	v_mov_b32_e32 v105, v57
	v_pk_fma_f32 v[76:77], v[84:85], v[84:85], v[76:77]
	v_add_f32_e32 v74, v78, v74
	v_pk_fma_f32 v[76:77], v[104:105], v[104:105], v[76:77]
	v_add_f32_e32 v74, v74, v75
	v_add_f32_e32 v74, v74, v76
	v_add_f32_e32 v74, v74, v77
	v_mov_b32_e32 v75, v74
	s_nop 1
	v_permlane32_swap_b32_e32 v75, v74
	v_add_f32_e32 v74, v74, v75
	v_mov_b32_e32 v75, v74
	s_nop 1
	v_permlane16_swap_b32_e32 v75, v74
	v_add_f32_e32 v74, v74, v75
	s_nop 1
	v_add_f32_dpp v74, v74, v74 row_ror:8 row_mask:0xf bank_mask:0xf
	s_nop 1
	v_add_f32_dpp v74, v74, v74 row_ror:4 row_mask:0xf bank_mask:0xf
	s_nop 1
	v_add_f32_dpp v74, v74, v74 quad_perm:[2,3,0,1] row_mask:0xf bank_mask:0xf
	s_nop 1
	v_add_f32_dpp v74, v74, v74 quad_perm:[1,0,3,2] row_mask:0xf bank_mask:0xf
	s_nop 1
	v_fmamk_f32 v74, v74, 0x3a000000, v41
	v_mul_f32_e32 v75, 0x4b800000, v74
	v_cmp_gt_f32_e32 vcc, s4, v74
	s_nop 1
	v_cndmask_b32_e32 v74, v74, v75, vcc
	v_rsq_f32_e32 v74, v74
	s_nop 0
	v_mul_f32_e32 v75, 0x45800000, v74
	v_cndmask_b32_e32 v74, v74, v75, vcc
	v_pk_mul_f32 v[62:63], v[62:63], v[74:75] op_sel_hi:[1,0]
	v_pk_mul_f32 v[64:65], v[64:65], v[74:75] op_sel_hi:[1,0]
	v_pk_mul_f32 v[58:59], v[58:59], v[74:75] op_sel_hi:[1,0]
	v_pk_mul_f32 v[60:61], v[60:61], v[74:75] op_sel_hi:[1,0]
	v_pk_mul_f32 v[66:67], v[66:67], v[74:75] op_sel_hi:[1,0]
	v_pk_mul_f32 v[68:69], v[68:69], v[74:75] op_sel_hi:[1,0]
	v_pk_mul_f32 v[70:71], v[70:71], v[74:75] op_sel_hi:[1,0]
	v_pk_mul_f32 v[72:73], v[72:73], v[74:75] op_sel_hi:[1,0]
	v_pk_mul_f32 v[76:77], v[32:33], v[74:75] op_sel_hi:[1,0]
	v_pk_mul_f32 v[78:79], v[34:35], v[74:75] op_sel_hi:[1,0]
	v_pk_mul_f32 v[80:81], v[36:37], v[74:75] op_sel_hi:[1,0]
	v_pk_mul_f32 v[82:83], v[38:39], v[74:75] op_sel_hi:[1,0]
	v_pk_mul_f32 v[84:85], v[50:51], v[74:75] op_sel_hi:[1,0]
	v_pk_mul_f32 v[86:87], v[52:53], v[74:75] op_sel_hi:[1,0]
	v_pk_mul_f32 v[88:89], v[54:55], v[74:75] op_sel_hi:[1,0]
	v_pk_mul_f32 v[74:75], v[56:57], v[74:75] op_sel_hi:[1,0]
	v_pk_mul_f32 v[32:33], v[0:1], v[62:63]
	v_pk_mul_f32 v[34:35], v[2:3], v[64:65]
	v_pk_mul_f32 v[36:37], v[4:5], v[58:59]
	v_pk_mul_f32 v[38:39], v[6:7], v[60:61]
	v_pk_mul_f32 v[50:51], v[8:9], v[66:67]
	v_pk_mul_f32 v[52:53], v[10:11], v[68:69]
	v_pk_mul_f32 v[54:55], v[12:13], v[70:71]
	v_pk_mul_f32 v[56:57], v[14:15], v[72:73]
	v_pk_mul_f32 v[58:59], v[16:17], v[76:77]
	v_pk_mul_f32 v[60:61], v[18:19], v[78:79]
	v_pk_mul_f32 v[62:63], v[20:21], v[80:81]
	v_pk_mul_f32 v[64:65], v[22:23], v[82:83]
	v_pk_mul_f32 v[66:67], v[24:25], v[84:85]
	v_pk_mul_f32 v[68:69], v[26:27], v[86:87]
	v_pk_mul_f32 v[70:71], v[28:29], v[88:89]
	v_pk_mul_f32 v[72:73], v[30:31], v[74:75]
	global_store_dwordx4 v[42:43], v[32:35], off offset:-4096
	global_store_dwordx4 v[42:43], v[36:39], off offset:-3072
	global_store_dwordx4 v[42:43], v[50:53], off offset:-2048
	global_store_dwordx4 v[42:43], v[54:57], off offset:-1024
	global_store_dwordx4 v[42:43], v[58:61], off
	global_store_dwordx4 v[42:43], v[62:65], off offset:1024
	global_store_dwordx4 v[42:43], v[66:69], off offset:2048
	global_store_dwordx4 v[42:43], v[70:73], off offset:3072
	v_lshl_add_u64 v[42:43], v[42:43], 0, s[6:7]
	s_andn2_b64 exec, exec, s[2:3]
	s_cbranch_execnz .LBB0_1421
